# scan helper post-processing: the three late gamma ds_read_b128 issued together with the first five (landing in restored constant registers); on top of DPP partial sums, attention QK read-ahead, packed
# baseline (speedup 1.0000x reference)
; DI void sh_load(const ScanH& k, int nc, u32x4 (&st)[14]) {
;     const size_t o8 = (size_t)nc * 8192; const int ht = k.ht;
; #pragma unroll
;     for (int i = 0; i < 4; ++i) { const int id = ht + 256 * i, r = id >> 4, cc = id & 15; st[i] = *(const u32x4*)(k.WC + o8 + r * 128 + cc * 8); st[4 + i] = *(const u32x4*)(k.QD + o8 + r * 128 + cc * 8); }
; #pragma unroll
;     for (int i = 0; i < 4; ++i) { const int id = ht + 256 * i, r = id >> 3, cc = id & 7; st[8 + i] = *(const u32x4*)(k.KD + o8 + r * 64 + cc * 8); }
; #pragma unroll
;     for (int i = 0; i < 2; ++i) { const int id = ht + 256 * i, r = id >> 3, cc = id & 7; st[12 + i] = *(const u32x4*)(k.AT + (size_t)nc * 4096 + r * 64 + cc * 8); }
; }
; DI void sh_store(const ScanH& k, int bf, const u32x4 (&st)[14]) {
;     LAS unsigned char* B_ = k.lds + bf * SC_BUF; const int ht = k.ht;
; #pragma unroll
;     for (int i = 0; i < 4; ++i) { const int id = ht + 256 * i, r = id >> 4, cc = id & 15;
;         *(LAS u32x2*)(B_ + SC_W + r * 264 + cc * 16) = (u32x2){st[i].x, st[i].y}; *(LAS u32x2*)(B_ + SC_W + r * 264 + cc * 16 + 8) = (u32x2){st[i].z, st[i].w};
;         *(LAS u32x2*)(B_ + SC_Q + r * 264 + cc * 16) = (u32x2){st[4 + i].x, st[4 + i].y}; *(LAS u32x2*)(B_ + SC_Q + r * 264 + cc * 16 + 8) = (u32x2){st[4 + i].z, st[4 + i].w}; }
; #pragma unroll
;     for (int i = 0; i < 4; ++i) { const int id = ht + 256 * i, r = id >> 3, cc = id & 7;
;         *(LAS u32x2*)(B_ + SC_K + r * 136 + cc * 16) = (u32x2){st[8 + i].x, st[8 + i].y}; *(LAS u32x2*)(B_ + SC_K + r * 136 + cc * 16 + 8) = (u32x2){st[8 + i].z, st[8 + i].w}; }
; #pragma unroll
;     for (int i = 0; i < 2; ++i) { const int id = ht + 256 * i, r = id >> 3, cc = id & 7;
;         *(LAS u32x2*)(B_ + SC_A + r * 136 + cc * 16) = (u32x2){st[12 + i].x, st[12 + i].y}; *(LAS u32x2*)(B_ + SC_A + r * 136 + cc * 16 + 8) = (u32x2){st[12 + i].z, st[12 + i].w}; }
; DI void scan_helper_step(const ScanH& k, int n, u32x4 (&stL)[14], const u32x4 (&stS)[14]) {
;     LAS unsigned char* lds = k.lds; const int bf = n & 1, tokb = k.b * SEQ + n * 64;
;     u32x4 zz[4];
;     { const bf16_t* zp = k.Zg + (size_t)(tokb + k.pt) * 512 + k.h * 128 + 32 * k.pseg;
; #pragma unroll
;       for (int i = 0; i < 4; ++i) zz[i] = *(const u32x4*)(zp + 8 * i); }
;     sh_load(k, n + 2 < 128 ? n + 2 : 127, stL);
;     sh_store(k, bf ^ 1, stS);
;     SC_RAW_BARRIER();
.LBB0_198:
	v_ashrrev_i32_e32 v151, 31, v150
	v_add_u32_e32 v58, 64, v150
	v_ashrrev_i32_e32 v59, 31, v58
	v_lshlrev_b64 v[58:59], 10, v[58:59]
	v_lshl_add_u64 v[58:59], v[152:153], 0, v[58:59]
	global_load_dwordx4 v[236:239], v[58:59], off offset:48
	global_load_dwordx4 v[240:243], v[58:59], off offset:32
	global_load_dwordx4 v[244:247], v[58:59], off offset:16
	global_load_dwordx4 v[248:251], v[58:59], off
	s_add_i32 s24, s40, 2
	v_add_u32_e32 v186, 0xea00, v159
	s_min_u32 s14, s24, 0x7d
	s_waitcnt vmcnt(17)
	ds_write2_b64 v186, v[2:3], v[4:5] offset1:1
	v_add_u32_e32 v2, v180, v158
	s_lshl_b32 s41, s14, 13
	s_waitcnt vmcnt(16)
	ds_write2_b64 v2, v[10:11], v[12:13] offset1:1
	v_add_u32_e32 v2, 0xea00, v162
	s_addk_i32 s41, 0x4000
	s_waitcnt vmcnt(15)
	ds_write2_b64 v2, v[6:7], v[8:9] offset1:1
	v_add_u32_e32 v2, v180, v161
	s_lshl_b32 s44, s41, 1
	s_waitcnt vmcnt(14)
	ds_write2_b64 v2, v[18:19], v[20:21] offset1:1
	v_add_u32_e32 v2, 0xea00, v165
	s_add_u32 s14, s4, s44
	s_waitcnt vmcnt(13)
	ds_write2_b64 v2, v[14:15], v[16:17] offset1:1
	v_add_u32_e32 v2, v180, v164
	s_addc_u32 s15, s5, 0
	s_waitcnt vmcnt(12)
	ds_write2_b64 v2, v[26:27], v[28:29] offset1:1
	v_add_u32_e32 v2, 0xea00, v168
	s_add_u32 s42, s6, s44
	s_waitcnt vmcnt(11)
	ds_write2_b64 v2, v[22:23], v[24:25] offset1:1
	v_add_u32_e32 v2, v180, v167
	s_addc_u32 s43, s7, 0
	s_waitcnt vmcnt(10)
	ds_write2_b64 v2, v[30:31], v[32:33] offset1:1
	v_add_u32_e32 v2, v181, v170
	v_lshl_add_u64 v[58:59], s[14:15], 0, v[134:135]
	v_lshl_add_u64 v[66:67], s[14:15], 0, v[136:137]
	v_lshl_add_u64 v[74:75], s[14:15], 0, v[138:139]
	v_lshl_add_u64 v[82:83], s[14:15], 0, v[140:141]
	s_add_u32 s14, s8, s44
	s_waitcnt vmcnt(9)
	ds_write2_b64 v2, v[34:35], v[36:37] offset1:1
	v_add_u32_e32 v2, v181, v172
	s_addc_u32 s15, s9, 0
	s_waitcnt vmcnt(8)
	ds_write2_b64 v2, v[38:39], v[40:41] offset1:1
	v_add_u32_e32 v2, v181, v174
	v_lshl_add_u64 v[90:91], s[14:15], 0, v[142:143]
	v_lshl_add_u64 v[94:95], s[14:15], 0, v[144:145]
	v_lshl_add_u64 v[98:99], s[14:15], 0, v[146:147]
	v_lshl_add_u64 v[102:103], s[14:15], 0, v[148:149]
	s_add_u32 s14, s10, s41
	s_waitcnt vmcnt(7)
	ds_write2_b64 v2, v[42:43], v[44:45] offset1:1
	v_add_u32_e32 v2, v181, v176
	s_addc_u32 s15, s11, 0
	s_waitcnt vmcnt(6)
	ds_write2_b64 v2, v[46:47], v[48:49] offset1:1
	v_add_u32_e32 v2, v182, v170
	v_lshl_add_u64 v[62:63], s[42:43], 0, v[134:135]
	v_lshl_add_u64 v[70:71], s[42:43], 0, v[136:137]
	v_lshl_add_u64 v[78:79], s[42:43], 0, v[138:139]
	v_lshl_add_u64 v[86:87], s[42:43], 0, v[140:141]
	v_mov_b32_e32 v157, v1
	v_lshl_add_u64 v[106:107], s[14:15], 0, v[142:143]
	v_lshl_add_u64 v[110:111], s[14:15], 0, v[144:145]
	s_waitcnt vmcnt(5)
	ds_write2_b64 v2, v[50:51], v[52:53] offset1:1
	v_add_u32_e32 v2, v182, v172
	v_lshl_add_u64 v[58:59], v[58:59], 0, v[0:1]
	v_lshl_add_u64 v[62:63], v[62:63], 0, v[0:1]
	v_lshl_add_u64 v[66:67], v[66:67], 0, v[0:1]
	v_lshl_add_u64 v[70:71], v[70:71], 0, v[0:1]
	v_lshl_add_u64 v[74:75], v[74:75], 0, v[0:1]
	v_lshl_add_u64 v[78:79], v[78:79], 0, v[0:1]
	v_lshl_add_u64 v[82:83], v[82:83], 0, v[0:1]
	v_lshl_add_u64 v[86:87], v[86:87], 0, v[0:1]
	v_lshl_add_u64 v[90:91], v[90:91], 0, v[156:157]
	v_lshl_add_u64 v[94:95], v[94:95], 0, v[156:157]
	v_lshl_add_u64 v[98:99], v[98:99], 0, v[156:157]
	v_lshl_add_u64 v[102:103], v[102:103], 0, v[156:157]
	v_lshl_add_u64 v[106:107], v[106:107], 0, v[156:157]
	v_lshl_add_u64 v[110:111], v[110:111], 0, v[156:157]
	s_waitcnt vmcnt(4)
	ds_write2_b64 v2, v[54:55], v[56:57] offset1:1
	global_load_dwordx4 v[58:61], v[58:59], off
	s_add_i32 s14, s40, 3
	global_load_dwordx4 v[62:65], v[62:63], off
	s_min_u32 s14, s14, 0x7d
	global_load_dwordx4 v[66:69], v[66:67], off
	s_lshl_b32 s14, s14, 13
	global_load_dwordx4 v[70:73], v[70:71], off
	v_lshlrev_b32_e32 v228, 16, v118
	global_load_dwordx4 v[74:77], v[74:75], off
	v_and_b32_e32 v229, 0xffff0000, v118
	global_load_dwordx4 v[78:81], v[78:79], off
	v_lshlrev_b32_e32 v56, 16, v128
	global_load_dwordx4 v[82:85], v[82:83], off
	v_and_b32_e32 v57, 0xffff0000, v128
	global_load_dwordx4 v[86:89], v[86:87], off
	v_lshlrev_b32_e32 v192, 16, v127
	global_load_dwordx4 v[90:93], v[90:91], off
	v_and_b32_e32 v193, 0xffff0000, v127
	global_load_dwordx4 v[94:97], v[94:95], off
	v_lshlrev_b32_e32 v202, 16, v126
	global_load_dwordx4 v[98:101], v[98:99], off
	v_and_b32_e32 v203, 0xffff0000, v126
	global_load_dwordx4 v[102:105], v[102:103], off
	v_lshlrev_b32_e32 v126, 16, v129
	global_load_dwordx4 v[106:109], v[106:107], off
	v_and_b32_e32 v127, 0xffff0000, v129
	global_load_dwordx4 v[110:113], v[110:111], off
	s_waitcnt lgkmcnt(0)
	s_barrier
; #define LAS __attribute__((address_space(3)))
; DI unsigned pk2(float lo, float hi) { f32x2 v = {lo, hi}; bf16x2_t b = __builtin_convertvector(v, bf16x2_t); return __builtin_bit_cast(unsigned, b); }
; DI float lo_bf(unsigned u) { return __uint_as_float(u << 16); }
; DI float hi_bf(unsigned u) { return __uint_as_float(u & 0xffff0000u); }
; DI void scan_helper_step(const ScanH& k, int n, u32x4 (&stL)[14], const u32x4 (&stS)[14]) {
;     ...
;     const LAS unsigned char* ob = lds + SC_O + bf * SC_OSZ + k.pt * 272 + k.pseg * 64;
;     const LAS float* gmL = (const LAS float*)(lds + SC_O + 2 * SC_OSZ + 512) + 32 * k.pseg;
;     u32x4 ov4[4];
; #pragma unroll
;     for (int i = 0; i < 4; ++i) ov4[i] = *(const LAS u32x4*)(ob + 16 * i);
;     float ss = 0.f;
; #pragma unroll
;     for (int i = 0; i < 4; ++i)
; #pragma unroll
;         for (int j = 0; j < 4; ++j) { const float a = lo_bf(ov4[i][j]), b2 = hi_bf(ov4[i][j]); ss += a * a + b2 * b2; }
;     ss += __shfl_xor(ss, 1); ss += __shfl_xor(ss, 2);
;     const float rs = __builtin_amdgcn_rsqf(ss * (1.f / 128.f) + RMS_EPS);
;     bf16_t* mp = k.MIX + (size_t)(tokb + k.pt) * DM + k.h * 128 + 32 * k.pseg;
; #pragma unroll
;     for (int i = 0; i < 4; ++i) { u32x4 res;
; #pragma unroll
;         for (int j = 0; j < 4; ++j) { const int e = 8 * i + 2 * j;
;             const float a0 = lo_bf(ov4[i][j]) * rs * gmL[e] * lo_bf(zz[i][j]), a1 = hi_bf(ov4[i][j]) * rs * gmL[e + 1] * hi_bf(zz[i][j]); res[j] = pk2(a0, a1); }
;         *(u32x4*)(mp + 8 * i) = res; }
	ds_read_b128 v[14:17], v183
	ds_read_b128 v[18:21], v183 offset:16
	ds_read_b128 v[22:25], v183 offset:32
	ds_read_b128 v[2:5], v183 offset:48
	v_lshlrev_b32_e32 v210, 16, v124
	s_waitcnt lgkmcnt(3)
	v_lshlrev_b32_e32 v188, 16, v15
	v_and_b32_e32 v189, 0xffff0000, v15
	s_waitcnt lgkmcnt(1)
	v_and_b32_e32 v13, 0xffff0000, v25
	v_and_b32_e32 v12, 0xffff0000, v24
	v_lshlrev_b32_e32 v11, 16, v25
	v_lshlrev_b32_e32 v10, 16, v24
	v_pk_mul_f32 v[6:7], v[12:13], v[12:13]
	s_waitcnt lgkmcnt(0)
	v_and_b32_e32 v9, 0xffff0000, v3
	v_and_b32_e32 v8, 0xffff0000, v2
	v_pk_fma_f32 v[40:41], v[10:11], v[10:11], v[6:7]
	v_lshlrev_b32_e32 v7, 16, v3
	v_lshlrev_b32_e32 v6, 16, v2
	v_pk_mul_f32 v[2:3], v[8:9], v[8:9]
	v_lshlrev_b32_e32 v198, 16, v14
	v_pk_fma_f32 v[42:43], v[6:7], v[6:7], v[2:3]
	v_lshlrev_b32_e32 v3, 16, v5
	v_lshlrev_b32_e32 v2, 16, v4
	v_and_b32_e32 v5, 0xffff0000, v5
	v_and_b32_e32 v4, 0xffff0000, v4
	v_pk_mul_f32 v[24:25], v[4:5], v[4:5]
	v_and_b32_e32 v199, 0xffff0000, v14
	v_pk_fma_f32 v[44:45], v[2:3], v[2:3], v[24:25]
	v_and_b32_e32 v25, 64, v230
	v_xor_b32_e32 v24, 1, v230
	v_add_u32_e32 v25, 64, v25
	v_cmp_lt_i32_e32 vcc, v24, v25
	v_lshlrev_b32_e32 v52, 16, v16
	v_and_b32_e32 v53, 0xffff0000, v16
	v_cndmask_b32_e32 v24, v230, v24, vcc
	v_lshlrev_b32_e32 v186, 2, v24
	v_xor_b32_e32 v24, 2, v230
	v_cmp_lt_i32_e32 vcc, v24, v25
	v_pk_mul_f32 v[190:191], v[188:189], v[188:189]
	v_pk_mul_f32 v[200:201], v[198:199], v[198:199]
	v_cndmask_b32_e32 v24, v230, v24, vcc
	v_lshlrev_b32_e32 v187, 2, v24
	v_lshlrev_b64 v[24:25], 11, v[150:151]
	v_lshlrev_b32_e32 v48, 16, v17
	v_and_b32_e32 v49, 0xffff0000, v17
	v_pk_mul_f32 v[54:55], v[52:53], v[52:53]
	v_add_f32_e32 v118, v190, v191
	v_add_f32_e32 v151, v200, v201
	v_pk_mul_f32 v[50:51], v[48:49], v[48:49]
	v_lshlrev_b32_e32 v218, 16, v18
	v_and_b32_e32 v219, 0xffff0000, v18
	v_add_f32_e32 v118, v151, v118
	v_add_f32_e32 v54, v54, v55
	v_lshlrev_b32_e32 v212, 16, v19
	v_and_b32_e32 v213, 0xffff0000, v19
	v_pk_mul_f32 v[18:19], v[218:219], v[218:219]
	v_add_f32_e32 v54, v54, v118
	v_add_f32_e32 v50, v50, v51
	v_lshlrev_b32_e32 v208, 16, v20
	v_and_b32_e32 v209, 0xffff0000, v20
	v_pk_mul_f32 v[214:215], v[212:213], v[212:213]
	v_add_f32_e32 v50, v50, v54
	v_add_f32_e32 v18, v18, v19
	v_lshlrev_b32_e32 v128, 16, v21
	v_and_b32_e32 v129, 0xffff0000, v21
	v_pk_mul_f32 v[20:21], v[208:209], v[208:209]
	v_add_f32_e32 v18, v18, v50
	v_add_f32_e32 v19, v214, v215
	v_pk_mul_f32 v[204:205], v[128:129], v[128:129]
	v_lshlrev_b32_e32 v224, 16, v22
	v_and_b32_e32 v225, 0xffff0000, v22
	v_add_f32_e32 v18, v19, v18
	v_add_f32_e32 v19, v20, v21
	v_and_b32_e32 v211, 0xffff0000, v124
	v_lshlrev_b32_e32 v216, 16, v123
	v_and_b32_e32 v217, 0xffff0000, v123
	v_lshlrev_b32_e32 v220, 16, v122
	v_and_b32_e32 v221, 0xffff0000, v122
	v_lshlrev_b32_e32 v122, 16, v125
	v_and_b32_e32 v123, 0xffff0000, v125
	v_lshlrev_b32_e32 v124, 16, v23
	v_and_b32_e32 v125, 0xffff0000, v23
	v_pk_mul_f32 v[22:23], v[224:225], v[224:225]
	v_add_f32_e32 v18, v19, v18
	v_add_f32_e32 v19, v204, v205
	v_pk_mul_f32 v[222:223], v[124:125], v[124:125]
	v_add_f32_e32 v18, v19, v18
	v_add_f32_e32 v19, v22, v23
	v_add_f32_e32 v18, v19, v18
	v_add_f32_e32 v19, v222, v223
	v_add_f32_e32 v18, v19, v18
	v_add_f32_e32 v18, v40, v18
	v_add_f32_e32 v18, v41, v18
	v_add_f32_e32 v18, v42, v18
	v_add_f32_e32 v18, v43, v18
	v_add_f32_e32 v18, v44, v18
	v_add_f32_e32 v18, v45, v18
	s_nop 1
	v_mov_b32_dpp v19, v18 quad_perm:[1,0,3,2] row_mask:0xf bank_mask:0xf
	v_lshl_add_u64 v[46:47], v[154:155], 0, v[24:25]
	ds_read_b128 v[24:27], v184
	ds_read_b128 v[28:31], v184 offset:16
	ds_read_b128 v[32:35], v184 offset:32
	ds_read_b128 v[36:39], v184 offset:48
	ds_read_b128 v[14:17], v184 offset:64
	ds_read_b128 v[130:133], v184 offset:80
	ds_read_b128 v[194:197], v184 offset:96
	ds_read_b128 v[232:235], v184 offset:112
	s_add_i32 s42, s14, 0x4000
	s_waitcnt lgkmcnt(5)
	v_add_f32_e32 v18, v18, v19
	s_nop 1
	v_mov_b32_dpp v19, v18 quad_perm:[2,3,0,1] row_mask:0xf bank_mask:0xf
	s_lshl_b32 s43, s42, 1
	s_add_u32 s14, s4, s43
	s_addc_u32 s15, s5, 0
	s_add_u32 s40, s6, s43
	s_waitcnt lgkmcnt(0)
	v_add_f32_e32 v18, v18, v19
	v_fmamk_f32 v18, v18, 0x3c000000, v231
	v_rsq_f32_e32 v22, v18
	s_addc_u32 s41, s7, 0
	v_pk_mul_f32 v[18:19], v[22:23], v[198:199] op_sel_hi:[0,1]
	v_pk_mul_f32 v[20:21], v[22:23], v[188:189] op_sel_hi:[0,1]
	v_pk_mul_f32 v[18:19], v[24:25], v[18:19]
	v_pk_mul_f32 v[20:21], v[26:27], v[20:21]
	v_pk_mul_f32 v[18:19], v[18:19], v[202:203]
	v_pk_mul_f32 v[20:21], v[20:21], v[192:193]
	v_cvt_pk_bf16_f32 v18, v18, v19
	v_cvt_pk_bf16_f32 v19, v20, v21
	v_pk_mul_f32 v[20:21], v[22:23], v[52:53] op_sel_hi:[0,1]
	v_pk_mul_f32 v[24:25], v[22:23], v[48:49] op_sel_hi:[0,1]
	v_pk_mul_f32 v[20:21], v[28:29], v[20:21]
	v_pk_mul_f32 v[24:25], v[30:31], v[24:25]
	v_pk_mul_f32 v[20:21], v[20:21], v[56:57]
	v_pk_mul_f32 v[24:25], v[24:25], v[126:127]
	v_cvt_pk_bf16_f32 v20, v20, v21
	v_cvt_pk_bf16_f32 v21, v24, v25
	global_store_dwordx4 v[46:47], v[18:21], off
	v_pk_mul_f32 v[24:25], v[22:23], v[128:129] op_sel_hi:[0,1]
	v_pk_mul_f32 v[24:25], v[38:39], v[24:25]
	v_pk_mul_f32 v[18:19], v[22:23], v[218:219] op_sel_hi:[0,1]
	v_pk_mul_f32 v[20:21], v[22:23], v[212:213] op_sel_hi:[0,1]
	v_pk_mul_f32 v[18:19], v[32:33], v[18:19]
	v_pk_mul_f32 v[20:21], v[34:35], v[20:21]
	v_pk_mul_f32 v[18:19], v[18:19], v[220:221]
	v_pk_mul_f32 v[20:21], v[20:21], v[216:217]
	v_cvt_pk_bf16_f32 v18, v18, v19
	v_cvt_pk_bf16_f32 v19, v20, v21
	v_pk_mul_f32 v[20:21], v[22:23], v[208:209] op_sel_hi:[0,1]
	v_pk_mul_f32 v[20:21], v[36:37], v[20:21]
	v_pk_mul_f32 v[24:25], v[24:25], v[122:123]
	v_pk_mul_f32 v[20:21], v[20:21], v[210:211]
	v_add_u32_e32 v188, 64, v150
	v_cvt_pk_bf16_f32 v20, v20, v21
	v_cvt_pk_bf16_f32 v21, v24, v25
	global_store_dwordx4 v[46:47], v[18:21], off offset:16
	v_ashrrev_i32_e32 v189, 31, v188
	v_lshl_add_u64 v[30:31], s[40:41], 0, v[140:141]
	v_pk_mul_f32 v[18:19], v[22:23], v[224:225] op_sel_hi:[0,1]
	v_pk_mul_f32 v[14:15], v[18:19], v[14:15]
	v_pk_mul_f32 v[18:19], v[22:23], v[124:125] op_sel_hi:[0,1]
	v_pk_mul_f32 v[16:17], v[18:19], v[16:17]
	v_lshlrev_b32_e32 v18, 16, v119
	v_and_b32_e32 v19, 0xffff0000, v119
	v_pk_mul_f32 v[14:15], v[14:15], v[228:229]
	v_pk_mul_f32 v[16:17], v[16:17], v[18:19]
	v_cvt_pk_bf16_f32 v14, v14, v15
	v_cvt_pk_bf16_f32 v15, v16, v17
	v_mov_b32_e32 v16, v10
	v_mov_b32_e32 v17, v12
	v_pk_mul_f32 v[20:21], v[22:23], v[16:17] op_sel_hi:[0,1]
	v_mov_b32_e32 v12, v11
	v_pk_mul_f32 v[10:11], v[22:23], v[12:13] op_sel_hi:[0,1]
	v_lshlrev_b32_e32 v12, 16, v121
	v_and_b32_e32 v13, 0xffff0000, v121
	s_waitcnt lgkmcnt(0)
; DI void sh_load(const ScanH& k, int nc, u32x4 (&st)[14]) {
;     const size_t o8 = (size_t)nc * 8192; const int ht = k.ht;
; #pragma unroll
;     for (int i = 0; i < 4; ++i) { const int id = ht + 256 * i, r = id >> 4, cc = id & 15; st[i] = *(const u32x4*)(k.WC + o8 + r * 128 + cc * 8); st[4 + i] = *(const u32x4*)(k.QD + o8 + r * 128 + cc * 8); }
; #pragma unroll
;     for (int i = 0; i < 4; ++i) { const int id = ht + 256 * i, r = id >> 3, cc = id & 7; st[8 + i] = *(const u32x4*)(k.KD + o8 + r * 64 + cc * 8); }
; #pragma unroll
;     for (int i = 0; i < 2; ++i) { const int id = ht + 256 * i, r = id >> 3, cc = id & 7; st[12 + i] = *(const u32x4*)(k.AT + (size_t)nc * 4096 + r * 64 + cc * 8); }
; }
; DI void sh_store(const ScanH& k, int bf, const u32x4 (&st)[14]) {
;     LAS unsigned char* B_ = k.lds + bf * SC_BUF; const int ht = k.ht;
; #pragma unroll
;     for (int i = 0; i < 4; ++i) { const int id = ht + 256 * i, r = id >> 4, cc = id & 15;
;         *(LAS u32x2*)(B_ + SC_W + r * 264 + cc * 16) = (u32x2){st[i].x, st[i].y}; *(LAS u32x2*)(B_ + SC_W + r * 264 + cc * 16 + 8) = (u32x2){st[i].z, st[i].w};
;         *(LAS u32x2*)(B_ + SC_Q + r * 264 + cc * 16) = (u32x2){st[4 + i].x, st[4 + i].y}; *(LAS u32x2*)(B_ + SC_Q + r * 264 + cc * 16 + 8) = (u32x2){st[4 + i].z, st[4 + i].w}; }
; #pragma unroll
;     for (int i = 0; i < 4; ++i) { const int id = ht + 256 * i, r = id >> 3, cc = id & 7;
;         *(LAS u32x2*)(B_ + SC_K + r * 136 + cc * 16) = (u32x2){st[8 + i].x, st[8 + i].y}; *(LAS u32x2*)(B_ + SC_K + r * 136 + cc * 16 + 8) = (u32x2){st[8 + i].z, st[8 + i].w}; }
; #pragma unroll
;     for (int i = 0; i < 2; ++i) { const int id = ht + 256 * i, r = id >> 3, cc = id & 7;
;         *(LAS u32x2*)(B_ + SC_A + r * 136 + cc * 16) = (u32x2){st[12 + i].x, st[12 + i].y}; *(LAS u32x2*)(B_ + SC_A + r * 136 + cc * 16 + 8) = (u32x2){st[12 + i].z, st[12 + i].w}; }
; }
; DI void scan_helper_step(const ScanH& k, int n, u32x4 (&stL)[14], const u32x4 (&stS)[14]) {
;     LAS unsigned char* lds = k.lds; const int bf = n & 1, tokb = k.b * SEQ + n * 64;
;     u32x4 zz[4];
;     { const bf16_t* zp = k.Zg + (size_t)(tokb + k.pt) * 512 + k.h * 128 + 32 * k.pseg;
; #pragma unroll
;       for (int i = 0; i < 4; ++i) zz[i] = *(const u32x4*)(zp + 8 * i); }
;     sh_load(k, n + 2 < 128 ? n + 2 : 127, stL);
;     sh_store(k, bf ^ 1, stS);
;     SC_RAW_BARRIER();
	v_pk_mul_f32 v[16:17], v[20:21], v[130:131]
	v_lshlrev_b32_e32 v20, 16, v120
	v_and_b32_e32 v21, 0xffff0000, v120
	v_pk_mul_f32 v[10:11], v[10:11], v[132:133]
	v_pk_mul_f32 v[16:17], v[16:17], v[20:21]
	v_pk_mul_f32 v[10:11], v[10:11], v[12:13]
	v_cvt_pk_bf16_f32 v16, v16, v17
	v_cvt_pk_bf16_f32 v17, v10, v11
	v_mov_b32_e32 v10, v6
	v_mov_b32_e32 v11, v8
	global_store_dwordx4 v[46:47], v[14:17], off offset:32
	v_mov_b32_e32 v8, v7
	v_pk_mul_f32 v[8:9], v[22:23], v[8:9] op_sel_hi:[0,1]
	v_pk_mul_f32 v[14:15], v[22:23], v[10:11] op_sel_hi:[0,1]
	v_lshl_add_u64 v[30:31], v[30:31], 0, v[0:1]
	v_add_u32_e32 v150, 0x80, v150
	s_waitcnt lgkmcnt(0)
	v_pk_mul_f32 v[10:11], v[14:15], v[194:195]
	v_lshlrev_b32_e32 v14, 16, v114
	v_and_b32_e32 v15, 0xffff0000, v114
	v_pk_mul_f32 v[10:11], v[10:11], v[14:15]
	v_pk_mul_f32 v[8:9], v[8:9], v[196:197]
	v_cvt_pk_bf16_f32 v6, v10, v11
	v_lshlrev_b32_e32 v10, 16, v115
	v_and_b32_e32 v11, 0xffff0000, v115
	v_pk_mul_f32 v[8:9], v[8:9], v[10:11]
	v_lshl_add_u64 v[14:15], s[40:41], 0, v[136:137]
	v_cvt_pk_bf16_f32 v7, v8, v9
	v_mov_b32_e32 v8, v2
	v_mov_b32_e32 v9, v4
	v_pk_mul_f32 v[12:13], v[22:23], v[8:9] op_sel_hi:[0,1]
	v_mov_b32_e32 v4, v3
	v_pk_mul_f32 v[2:3], v[22:23], v[4:5] op_sel_hi:[0,1]
	v_lshlrev_b32_e32 v4, 16, v117
	v_and_b32_e32 v5, 0xffff0000, v117
	s_waitcnt lgkmcnt(0)
	v_pk_mul_f32 v[8:9], v[12:13], v[232:233]
	v_lshlrev_b32_e32 v12, 16, v116
	v_and_b32_e32 v13, 0xffff0000, v116
	v_pk_mul_f32 v[2:3], v[2:3], v[234:235]
	v_pk_mul_f32 v[8:9], v[8:9], v[12:13]
	v_pk_mul_f32 v[2:3], v[2:3], v[4:5]
	v_cvt_pk_bf16_f32 v8, v8, v9
	v_cvt_pk_bf16_f32 v9, v2, v3
	v_add_u32_e32 v2, 64, v188
	v_ashrrev_i32_e32 v3, 31, v2
	v_lshlrev_b64 v[2:3], 10, v[2:3]
	global_store_dwordx4 v[46:47], v[6:9], off offset:48
	v_lshl_add_u64 v[2:3], v[152:153], 0, v[2:3]
	global_load_dwordx4 v[114:117], v[2:3], off offset:48
	global_load_dwordx4 v[118:121], v[2:3], off offset:32
	global_load_dwordx4 v[122:125], v[2:3], off offset:16
	global_load_dwordx4 v[126:129], v[2:3], off
	v_lshl_add_u64 v[2:3], s[14:15], 0, v[134:135]
	v_lshl_add_u64 v[6:7], s[40:41], 0, v[134:135]
	v_lshl_add_u64 v[2:3], v[2:3], 0, v[0:1]
	v_lshl_add_u64 v[6:7], v[6:7], 0, v[0:1]
	global_load_dwordx4 v[2:5], v[2:3], off
	v_lshl_add_u64 v[14:15], v[14:15], 0, v[0:1]
	global_load_dwordx4 v[10:13], v[6:7], off
	v_lshl_add_u64 v[6:7], s[14:15], 0, v[136:137]
	v_lshl_add_u64 v[6:7], v[6:7], 0, v[0:1]
	global_load_dwordx4 v[6:9], v[6:7], off
	v_lshl_add_u64 v[22:23], s[40:41], 0, v[138:139]
	global_load_dwordx4 v[18:21], v[14:15], off
	v_lshl_add_u64 v[14:15], s[14:15], 0, v[138:139]
	v_lshl_add_u64 v[14:15], v[14:15], 0, v[0:1]
	v_lshl_add_u64 v[22:23], v[22:23], 0, v[0:1]
	global_load_dwordx4 v[14:17], v[14:15], off
	s_mov_b32 s40, s24
	global_load_dwordx4 v[26:29], v[22:23], off
	v_lshl_add_u64 v[22:23], s[14:15], 0, v[140:141]
	s_add_u32 s14, s8, s43
	s_addc_u32 s15, s9, 0
	v_lshl_add_u64 v[34:35], s[14:15], 0, v[142:143]
	v_lshl_add_u64 v[38:39], s[14:15], 0, v[144:145]
	v_lshl_add_u64 v[42:43], s[14:15], 0, v[146:147]
	v_lshl_add_u64 v[46:47], s[14:15], 0, v[148:149]
	s_add_u32 s14, s10, s42
	s_addc_u32 s15, s11, 0
	v_lshl_add_u64 v[50:51], s[14:15], 0, v[142:143]
	v_lshl_add_u64 v[54:55], s[14:15], 0, v[144:145]
	v_lshl_add_u64 v[22:23], v[22:23], 0, v[0:1]
	v_lshl_add_u64 v[34:35], v[34:35], 0, v[156:157]
	v_lshl_add_u64 v[38:39], v[38:39], 0, v[156:157]
	v_lshl_add_u64 v[42:43], v[42:43], 0, v[156:157]
	v_lshl_add_u64 v[46:47], v[46:47], 0, v[156:157]
	v_lshl_add_u64 v[50:51], v[50:51], 0, v[156:157]
	v_lshl_add_u64 v[54:55], v[54:55], 0, v[156:157]
	global_load_dwordx4 v[22:25], v[22:23], off
	s_cmpk_gt_u32 s24, 0x7d
	global_load_dwordx4 v[30:33], v[30:31], off
	s_waitcnt vmcnt(16)
	v_lshlrev_b32_e32 v228, 16, v240
	global_load_dwordx4 v[34:37], v[34:35], off
	v_and_b32_e32 v229, 0xffff0000, v240
	global_load_dwordx4 v[38:41], v[38:39], off
	v_lshlrev_b32_e32 v192, 16, v249
	global_load_dwordx4 v[42:45], v[42:43], off
	v_and_b32_e32 v193, 0xffff0000, v249
	global_load_dwordx4 v[46:49], v[46:47], off
	v_lshlrev_b32_e32 v202, 16, v248
	global_load_dwordx4 v[50:53], v[50:51], off
	v_and_b32_e32 v203, 0xffff0000, v248
	global_load_dwordx4 v[54:57], v[54:55], off
	s_waitcnt vmcnt(22)
	ds_write2_b64 v159, v[58:59], v[60:61] offset1:1
	ds_write2_b64 v160, v[62:63], v[64:65] offset1:1
	ds_write2_b64 v162, v[66:67], v[68:69] offset1:1
	ds_write2_b64 v163, v[70:71], v[72:73] offset1:1
	ds_write2_b64 v165, v[74:75], v[76:77] offset1:1
	ds_write2_b64 v166, v[78:79], v[80:81] offset1:1
	ds_write2_b64 v168, v[82:83], v[84:85] offset1:1
	ds_write2_b64 v169, v[86:87], v[88:89] offset1:1
	ds_write2_b64 v171, v[90:91], v[92:93] offset1:1
	ds_write2_b64 v173, v[94:95], v[96:97] offset1:1
	ds_write2_b64 v175, v[98:99], v[100:101] offset1:1
	ds_write2_b64 v177, v[102:103], v[104:105] offset1:1
	ds_write2_b64 v178, v[106:107], v[108:109] offset1:1
	ds_write2_b64 v179, v[110:111], v[112:113] offset1:1
	s_waitcnt lgkmcnt(0)
	s_barrier
; #define LAS __attribute__((address_space(3)))
; DI float lo_bf(unsigned u) { return __uint_as_float(u << 16); }
; DI float hi_bf(unsigned u) { return __uint_as_float(u & 0xffff0000u); }
; DI void scan_helper_step(const ScanH& k, int n, u32x4 (&stL)[14], const u32x4 (&stS)[14]) {
;     ...
;     const LAS unsigned char* ob = lds + SC_O + bf * SC_OSZ + k.pt * 272 + k.pseg * 64;
;     const LAS float* gmL = (const LAS float*)(lds + SC_O + 2 * SC_OSZ + 512) + 32 * k.pseg;
;     u32x4 ov4[4];
; #pragma unroll
;     for (int i = 0; i < 4; ++i) ov4[i] = *(const LAS u32x4*)(ob + 16 * i);
;     float ss = 0.f;
; #pragma unroll
;     for (int i = 0; i < 4; ++i)
; #pragma unroll
;         for (int j = 0; j < 4; ++j) { const float a = lo_bf(ov4[i][j]), b2 = hi_bf(ov4[i][j]); ss += a * a + b2 * b2; }
;     ss += __shfl_xor(ss, 1); ss += __shfl_xor(ss, 2);
;     const float rs = __builtin_amdgcn_rsqf(ss * (1.f / 128.f) + RMS_EPS);
	ds_read_b128 v[58:61], v185
	ds_read_b128 v[62:65], v185 offset:16
	ds_read_b128 v[66:69], v185 offset:32
	ds_read_b128 v[70:73], v185 offset:48
	v_lshlrev_b32_e32 v112, 16, v250
	s_waitcnt lgkmcnt(3)
	v_lshlrev_b32_e32 v198, 16, v58
	v_and_b32_e32 v199, 0xffff0000, v58
	s_waitcnt lgkmcnt(1)
	v_and_b32_e32 v87, 0xffff0000, v69
	v_and_b32_e32 v86, 0xffff0000, v68
	v_lshlrev_b32_e32 v85, 16, v69
	v_lshlrev_b32_e32 v84, 16, v68
	v_pk_mul_f32 v[68:69], v[86:87], v[86:87]
	s_waitcnt lgkmcnt(0)
	v_and_b32_e32 v93, 0xffff0000, v71
	v_and_b32_e32 v92, 0xffff0000, v70
	v_pk_fma_f32 v[88:89], v[84:85], v[84:85], v[68:69]
	v_lshlrev_b32_e32 v91, 16, v71
	v_lshlrev_b32_e32 v90, 16, v70
	v_pk_mul_f32 v[68:69], v[92:93], v[92:93]
	v_and_b32_e32 v99, 0xffff0000, v73
	v_and_b32_e32 v98, 0xffff0000, v72
	v_pk_fma_f32 v[94:95], v[90:91], v[90:91], v[68:69]
	v_lshlrev_b32_e32 v97, 16, v73
	v_lshlrev_b32_e32 v96, 16, v72
	v_pk_mul_f32 v[68:69], v[98:99], v[98:99]
	v_lshlrev_b32_e32 v108, 16, v60
	v_pk_fma_f32 v[100:101], v[96:97], v[96:97], v[68:69]
	v_lshlrev_b64 v[68:69], 11, v[188:189]
	v_lshlrev_b32_e32 v188, 16, v59
	v_and_b32_e32 v189, 0xffff0000, v59
	v_and_b32_e32 v109, 0xffff0000, v60
	v_pk_mul_f32 v[190:191], v[188:189], v[188:189]
	v_pk_mul_f32 v[200:201], v[198:199], v[198:199]
	v_lshlrev_b32_e32 v104, 16, v61
	v_and_b32_e32 v105, 0xffff0000, v61
	v_pk_mul_f32 v[110:111], v[108:109], v[108:109]
	v_add_f32_e32 v240, v190, v191
	v_add_f32_e32 v151, v200, v201
	v_pk_mul_f32 v[106:107], v[104:105], v[104:105]
	v_lshlrev_b32_e32 v218, 16, v62
	v_and_b32_e32 v219, 0xffff0000, v62
	v_add_f32_e32 v240, v151, v240
	v_add_f32_e32 v110, v110, v111
	v_lshlrev_b32_e32 v212, 16, v63
	v_and_b32_e32 v213, 0xffff0000, v63
	v_pk_mul_f32 v[62:63], v[218:219], v[218:219]
	v_add_f32_e32 v110, v110, v240
	v_add_f32_e32 v106, v106, v107
	v_lshlrev_b32_e32 v208, 16, v64
	v_and_b32_e32 v209, 0xffff0000, v64
	v_pk_mul_f32 v[214:215], v[212:213], v[212:213]
	v_add_f32_e32 v106, v106, v110
	v_add_f32_e32 v62, v62, v63
	v_and_b32_e32 v113, 0xffff0000, v250
	v_lshlrev_b32_e32 v248, 16, v251
	v_and_b32_e32 v249, 0xffff0000, v251
	v_lshlrev_b32_e32 v250, 16, v65
	v_and_b32_e32 v251, 0xffff0000, v65
	v_pk_mul_f32 v[64:65], v[208:209], v[208:209]
	v_add_f32_e32 v62, v62, v106
	v_add_f32_e32 v63, v214, v215
	v_pk_mul_f32 v[204:205], v[250:251], v[250:251]
	v_lshlrev_b32_e32 v224, 16, v66
	v_and_b32_e32 v225, 0xffff0000, v66
	v_add_f32_e32 v62, v63, v62
	v_add_f32_e32 v63, v64, v65
	v_lshlrev_b32_e32 v210, 16, v246
	v_and_b32_e32 v211, 0xffff0000, v246
	v_lshlrev_b32_e32 v216, 16, v245
	v_and_b32_e32 v217, 0xffff0000, v245
	v_lshlrev_b32_e32 v220, 16, v244
	v_and_b32_e32 v221, 0xffff0000, v244
	v_lshlrev_b32_e32 v244, 16, v247
	v_and_b32_e32 v245, 0xffff0000, v247
	v_lshlrev_b32_e32 v246, 16, v67
	v_and_b32_e32 v247, 0xffff0000, v67
	v_pk_mul_f32 v[66:67], v[224:225], v[224:225]
	v_add_f32_e32 v62, v63, v62
	v_add_f32_e32 v63, v204, v205
	v_pk_mul_f32 v[222:223], v[246:247], v[246:247]
	v_add_f32_e32 v62, v63, v62
	v_add_f32_e32 v63, v66, v67
	v_add_f32_e32 v62, v63, v62
	v_add_f32_e32 v63, v222, v223
	v_add_f32_e32 v62, v63, v62
	v_add_f32_e32 v62, v88, v62
	v_add_f32_e32 v62, v89, v62
	v_add_f32_e32 v62, v94, v62
	v_add_f32_e32 v62, v95, v62
	v_add_f32_e32 v62, v100, v62
	v_add_f32_e32 v62, v101, v62
	s_nop 1
	v_mov_b32_dpp v63, v62 quad_perm:[1,0,3,2] row_mask:0xf bank_mask:0xf
	v_lshl_add_u64 v[102:103], v[154:155], 0, v[68:69]
	ds_read_b128 v[68:71], v184
	ds_read_b128 v[72:75], v184 offset:16
	ds_read_b128 v[76:79], v184 offset:32
	ds_read_b128 v[80:83], v184 offset:48
	ds_read_b128 v[58:61], v184 offset:64
	ds_read_b128 v[130:133], v184 offset:80
	ds_read_b128 v[194:197], v184 offset:96
	ds_read_b128 v[232:235], v184 offset:112
	s_waitcnt lgkmcnt(5)
	v_add_f32_e32 v62, v62, v63
	s_nop 1
	v_mov_b32_dpp v63, v62 quad_perm:[2,3,0,1] row_mask:0xf bank_mask:0xf
	s_waitcnt lgkmcnt(0)
; DI unsigned pk2(float lo, float hi) { f32x2 v = {lo, hi}; bf16x2_t b = __builtin_convertvector(v, bf16x2_t); return __builtin_bit_cast(unsigned, b); }
; DI float lo_bf(unsigned u) { return __uint_as_float(u << 16); }
; DI float hi_bf(unsigned u) { return __uint_as_float(u & 0xffff0000u); }
; DI void scan_helper_step(const ScanH& k, int n, u32x4 (&stL)[14], const u32x4 (&stS)[14]) {
;     ...
;     const float rs = __builtin_amdgcn_rsqf(ss * (1.f / 128.f) + RMS_EPS);
;     bf16_t* mp = k.MIX + (size_t)(tokb + k.pt) * DM + k.h * 128 + 32 * k.pseg;
; #pragma unroll
;     for (int i = 0; i < 4; ++i) { u32x4 res;
; #pragma unroll
;         for (int j = 0; j < 4; ++j) { const int e = 8 * i + 2 * j;
;             const float a0 = lo_bf(ov4[i][j]) * rs * gmL[e] * lo_bf(zz[i][j]), a1 = hi_bf(ov4[i][j]) * rs * gmL[e + 1] * hi_bf(zz[i][j]); res[j] = pk2(a0, a1); }
;         *(u32x4*)(mp + 8 * i) = res; }
; DI void scan_item(LAS unsigned char* lds, const Ctx& c, int l, int bh) {
;     ...
;         for (int n = 0; n < 128; n += 2) {
;             scan_helper_step(k, n, stA, stB);
;             scan_helper_step(k, n + 1, stB, stA);
;         }
	v_add_f32_e32 v62, v62, v63
	v_fmamk_f32 v62, v62, 0x3c000000, v231
	v_rsq_f32_e32 v66, v62
	s_nop 0
	v_pk_mul_f32 v[62:63], v[66:67], v[198:199] op_sel_hi:[0,1]
	v_pk_mul_f32 v[64:65], v[66:67], v[188:189] op_sel_hi:[0,1]
	v_pk_mul_f32 v[62:63], v[68:69], v[62:63]
	v_pk_mul_f32 v[64:65], v[70:71], v[64:65]
	v_pk_mul_f32 v[62:63], v[62:63], v[202:203]
	v_pk_mul_f32 v[64:65], v[64:65], v[192:193]
	v_cvt_pk_bf16_f32 v62, v62, v63
	v_cvt_pk_bf16_f32 v63, v64, v65
	v_pk_mul_f32 v[64:65], v[66:67], v[108:109] op_sel_hi:[0,1]
	v_pk_mul_f32 v[68:69], v[66:67], v[104:105] op_sel_hi:[0,1]
	v_pk_mul_f32 v[64:65], v[72:73], v[64:65]
	v_pk_mul_f32 v[68:69], v[74:75], v[68:69]
	v_pk_mul_f32 v[64:65], v[64:65], v[112:113]
	v_pk_mul_f32 v[68:69], v[68:69], v[248:249]
	v_cvt_pk_bf16_f32 v64, v64, v65
	v_cvt_pk_bf16_f32 v65, v68, v69
	global_store_dwordx4 v[102:103], v[62:65], off
	v_pk_mul_f32 v[68:69], v[66:67], v[250:251] op_sel_hi:[0,1]
	v_pk_mul_f32 v[68:69], v[82:83], v[68:69]
	v_pk_mul_f32 v[62:63], v[66:67], v[218:219] op_sel_hi:[0,1]
	v_pk_mul_f32 v[64:65], v[66:67], v[212:213] op_sel_hi:[0,1]
	v_pk_mul_f32 v[62:63], v[76:77], v[62:63]
	v_pk_mul_f32 v[64:65], v[78:79], v[64:65]
	v_pk_mul_f32 v[62:63], v[62:63], v[220:221]
	v_pk_mul_f32 v[64:65], v[64:65], v[216:217]
	v_cvt_pk_bf16_f32 v62, v62, v63
	v_cvt_pk_bf16_f32 v63, v64, v65
	v_pk_mul_f32 v[64:65], v[66:67], v[208:209] op_sel_hi:[0,1]
	v_pk_mul_f32 v[64:65], v[80:81], v[64:65]
	v_pk_mul_f32 v[68:69], v[68:69], v[244:245]
	v_pk_mul_f32 v[64:65], v[64:65], v[210:211]
	s_nop 0
	v_cvt_pk_bf16_f32 v64, v64, v65
	v_cvt_pk_bf16_f32 v65, v68, v69
	global_store_dwordx4 v[102:103], v[62:65], off offset:16
	s_nop 1
	v_pk_mul_f32 v[62:63], v[66:67], v[224:225] op_sel_hi:[0,1]
	v_pk_mul_f32 v[58:59], v[58:59], v[62:63]
	v_pk_mul_f32 v[62:63], v[66:67], v[246:247] op_sel_hi:[0,1]
	v_pk_mul_f32 v[60:61], v[62:63], v[60:61]
	v_lshlrev_b32_e32 v62, 16, v241
	v_and_b32_e32 v63, 0xffff0000, v241
	v_pk_mul_f32 v[58:59], v[58:59], v[228:229]
	v_pk_mul_f32 v[60:61], v[60:61], v[62:63]
	v_cvt_pk_bf16_f32 v58, v58, v59
	v_cvt_pk_bf16_f32 v59, v60, v61
	v_mov_b32_e32 v60, v84
	v_mov_b32_e32 v61, v86
	v_pk_mul_f32 v[64:65], v[66:67], v[60:61] op_sel_hi:[0,1]
	v_mov_b32_e32 v86, v85
	s_waitcnt lgkmcnt(0)
	v_pk_mul_f32 v[60:61], v[64:65], v[130:131]
	v_lshlrev_b32_e32 v64, 16, v242
	v_and_b32_e32 v65, 0xffff0000, v242
	v_pk_mul_f32 v[60:61], v[60:61], v[64:65]
	v_pk_mul_f32 v[64:65], v[66:67], v[86:87] op_sel_hi:[0,1]
	v_pk_mul_f32 v[62:63], v[64:65], v[132:133]
	v_lshlrev_b32_e32 v64, 16, v243
	v_and_b32_e32 v65, 0xffff0000, v243
	v_pk_mul_f32 v[62:63], v[62:63], v[64:65]
	v_cvt_pk_bf16_f32 v60, v60, v61
	v_cvt_pk_bf16_f32 v61, v62, v63
	global_store_dwordx4 v[102:103], v[58:61], off offset:32
	s_nop 1
	v_mov_b32_e32 v58, v90
	v_mov_b32_e32 v59, v92
	v_pk_mul_f32 v[62:63], v[66:67], v[58:59] op_sel_hi:[0,1]
	v_mov_b32_e32 v92, v91
	s_waitcnt lgkmcnt(0)
	v_pk_mul_f32 v[58:59], v[62:63], v[194:195]
	v_lshlrev_b32_e32 v62, 16, v236
	v_and_b32_e32 v63, 0xffff0000, v236
	v_pk_mul_f32 v[58:59], v[58:59], v[62:63]
	v_pk_mul_f32 v[62:63], v[66:67], v[92:93] op_sel_hi:[0,1]
	v_pk_mul_f32 v[60:61], v[62:63], v[196:197]
	v_lshlrev_b32_e32 v62, 16, v237
	v_and_b32_e32 v63, 0xffff0000, v237
	v_pk_mul_f32 v[60:61], v[60:61], v[62:63]
	v_cvt_pk_bf16_f32 v58, v58, v59
	v_cvt_pk_bf16_f32 v59, v60, v61
	v_mov_b32_e32 v60, v96
	v_mov_b32_e32 v61, v98
	v_pk_mul_f32 v[64:65], v[66:67], v[60:61] op_sel_hi:[0,1]
	v_mov_b32_e32 v98, v97
	s_waitcnt lgkmcnt(0)
	v_pk_mul_f32 v[60:61], v[64:65], v[232:233]
	v_lshlrev_b32_e32 v64, 16, v238
	v_and_b32_e32 v65, 0xffff0000, v238
	v_pk_mul_f32 v[60:61], v[60:61], v[64:65]
	v_pk_mul_f32 v[64:65], v[66:67], v[98:99] op_sel_hi:[0,1]
	v_pk_mul_f32 v[62:63], v[64:65], v[234:235]
	v_lshlrev_b32_e32 v64, 16, v239
	v_and_b32_e32 v65, 0xffff0000, v239
	v_pk_mul_f32 v[62:63], v[62:63], v[64:65]
	v_cvt_pk_bf16_f32 v60, v60, v61
	v_cvt_pk_bf16_f32 v61, v62, v63
	global_store_dwordx4 v[102:103], v[58:61], off offset:48
	s_cbranch_scc0 .LBB0_198
	s_waitcnt vmcnt(0)
	v_mov_b32_e32 v130, v1
	v_mov_b32_e32 v131, v1
	v_mov_b32_e32 v132, v1
	v_mov_b32_e32 v133, v1
	v_mov_b64_e32 v[194:195], 0x200
	v_mov_b64_e32 v[196:197], 0x1ff
	v_mov_b64_e32 v[232:233], 0x17f
	v_mov_b32_e32 v234, 0xc00
	v_mov_b32_e32 v235, 1
	v_mov_b64_e32 v[250:251], 0xaff
